# P0 x-norm: one counted wait per row pair placed before the next pair's loads are issued (the compiler's counts made it wait for the loads it had just issued)
# speedup vs baseline: 1.0113x; 1.0055x over previous
.LBB0_202:
	s_waitcnt vmcnt(7)
	v_mov_b32_e32 v2, s0
	v_mov_b32_e32 v3, s1
	v_mov_b32_e32 v0, s0
	v_mov_b32_e32 v1, s1
	v_readfirstlane_b32 s8, v2
	v_readfirstlane_b32 s9, v3
	v_mov_b32_e32 v2, s0
	v_mov_b32_e32 v3, s1
	s_cmpk_gt_i32 s6, 0x7fff
	v_readfirstlane_b32 s4, v2
	v_readfirstlane_b32 s5, v3
	v_readfirstlane_b32 s10, v0
	v_readfirstlane_b32 s11, v1
	s_cbranch_scc1 .LBB0_219
	s_load_dwordx2 s[12:13], s[10:11], 0xc0
	s_load_dwordx2 s[14:15], s[8:9], 0x0
	v_mov_b32_e32 v73, 0
	v_mov_b32_e32 v71, v73
	s_mul_i32 s25, s33, 40
	s_waitcnt lgkmcnt(0)
	s_add_u32 s22, s12, 0x3720c00
	s_addc_u32 s23, s13, 0
	s_add_i32 s7, s6, s26
	s_cmp_lt_i32 s7, 0x8000
	s_cselect_b32 s8, s7, s6
	s_ashr_i32 s7, s6, 31
	v_lshl_add_u64 v[64:65], s[14:15], 0, v[72:73]
	s_lshl_b64 s[10:11], s[6:7], 12
	s_ashr_i32 s9, s8, 31
	s_waitcnt vmcnt(3)
	v_lshl_add_u64 v[16:17], v[64:65], 0, s[10:11]
	s_lshl_b64 s[10:11], s[8:9], 12
	v_lshl_add_u64 v[32:33], v[64:65], 0, s[10:11]
	global_load_dwordx4 v[0:3], v[16:17], off nt
	global_load_dwordx4 v[4:7], v[16:17], off offset:1024 nt
	global_load_dwordx4 v[8:11], v[16:17], off offset:2048 nt
	global_load_dwordx4 v[12:15], v[16:17], off offset:3072 nt
	s_nop 0
	global_load_dwordx4 v[16:19], v[32:33], off nt
	global_load_dwordx4 v[20:23], v[32:33], off offset:1024 nt
	global_load_dwordx4 v[24:27], v[32:33], off offset:2048 nt
	global_load_dwordx4 v[28:31], v[32:33], off offset:3072 nt
	s_load_dwordx2 s[4:5], s[4:5], 0xc0
	s_lshl_b32 s24, s33, 5
	s_mul_i32 s26, s33, 24
	v_mov_b32_e32 v69, 0x358637bd
	s_mov_b32 s14, s6
	s_waitcnt lgkmcnt(0)
	v_lshl_add_u64 v[32:33], s[4:5], 0, v[70:71]
	s_mov_b64 s[4:5], 0x4000000
	v_lshl_add_u64 v[66:67], v[32:33], 0, s[4:5]
	v_mbcnt_lo_u32_b32 v32, -1, 0
	v_cmp_eq_u32_e64 s[4:5], 0, v86
	v_mbcnt_hi_u32_b32 v68, -1, v32
	s_waitcnt vmcnt(0)
	s_branch .LBB0_206

.LBB0_206:
	s_waitcnt vmcnt(10)
	s_add_i32 s16, s6, s3
	s_cmp_lt_i32 s16, 0x8000
	s_cselect_b64 s[18:19], -1, 0
	s_cmpk_gt_i32 s16, 0x7fff
	s_cbranch_scc1 .LBB0_208
	s_add_i32 s7, s26, s6
	s_cmp_lt_i32 s7, 0x8000
	s_cselect_b32 s10, s7, s16
	s_ashr_i32 s17, s16, 31
	s_lshl_b64 s[12:13], s[16:17], 12
	s_ashr_i32 s11, s10, 31
	v_lshl_add_u64 v[48:49], v[64:65], 0, s[12:13]
	s_lshl_b64 s[12:13], s[10:11], 12
	s_waitcnt lgkmcnt(0)
	v_lshl_add_u64 v[70:71], v[64:65], 0, s[12:13]
	global_load_dwordx4 v[32:35], v[48:49], off nt
	global_load_dwordx4 v[36:39], v[48:49], off offset:1024 nt
	global_load_dwordx4 v[40:43], v[48:49], off offset:2048 nt
	global_load_dwordx4 v[44:47], v[48:49], off offset:3072 nt
	s_nop 0
	global_load_dwordx4 v[48:51], v[70:71], off nt
	global_load_dwordx4 v[52:55], v[70:71], off offset:1024 nt
	global_load_dwordx4 v[56:59], v[70:71], off offset:2048 nt
	global_load_dwordx4 v[60:63], v[70:71], off offset:3072 nt
	s_mov_b32 s12, s16
.LBB0_208:
	v_mul_f32_e32 v70, v1, v1
	s_waitcnt lgkmcnt(0)
	v_mul_f32_e32 v71, v3, v3
	v_fmac_f32_e32 v70, v0, v0
	v_fmac_f32_e32 v71, v2, v2
	v_add_f32_e32 v70, v70, v71
	v_mul_f32_e32 v71, v5, v5
	v_mul_f32_e32 v72, v7, v7
	v_fmac_f32_e32 v71, v4, v4
	v_fmac_f32_e32 v72, v6, v6
	v_add_f32_e32 v71, v71, v72
	v_add_f32_e32 v70, v70, v71
	v_mul_f32_e32 v71, v9, v9
	v_mul_f32_e32 v72, v11, v11
	v_fmac_f32_e32 v71, v8, v8
	v_fmac_f32_e32 v72, v10, v10
	v_add_f32_e32 v71, v71, v72
	v_add_f32_e32 v70, v71, v70
	v_mul_f32_e32 v71, v13, v13
	v_mul_f32_e32 v72, v15, v15
	v_fmac_f32_e32 v71, v12, v12
	v_fmac_f32_e32 v72, v14, v14
	v_add_f32_e32 v71, v71, v72
	v_add_f32_e32 v71, v71, v70
	v_and_b32_e32 v70, 64, v68
	v_add_u32_e32 v78, 64, v70
	v_xor_b32_e32 v70, 1, v68
	v_cmp_lt_i32_e32 vcc, v70, v78
	s_ashr_i32 s15, s14, 31
	s_lshl_b64 s[20:21], s[14:15], 11
	v_cndmask_b32_e32 v70, v68, v70, vcc
	v_lshlrev_b32_e32 v70, 2, v70
	ds_bpermute_b32 v72, v70, v71
	v_lshl_add_u64 v[80:81], v[66:67], 0, s[20:21]
	v_cvt_pk_bf16_f32 v76, v0, v1
	v_cvt_pk_bf16_f32 v77, v2, v3
	global_store_dwordx2 v[80:81], v[76:77], off nt
	s_waitcnt lgkmcnt(0)
	v_add_f32_e32 v72, v71, v72
	v_xor_b32_e32 v71, 2, v68
	v_cmp_lt_i32_e32 vcc, v71, v78
	v_cvt_pk_bf16_f32 v76, v4, v5
	v_cvt_pk_bf16_f32 v77, v6, v7
	global_store_dwordx2 v[80:81], v[76:77], off offset:512 nt
	v_xor_b32_e32 v76, 32, v68
	v_cndmask_b32_e32 v71, v68, v71, vcc
	v_lshlrev_b32_e32 v71, 2, v71
	ds_bpermute_b32 v74, v71, v72
	v_cvt_pk_bf16_f32 v82, v8, v9
	v_cvt_pk_bf16_f32 v83, v10, v11
	global_store_dwordx2 v[80:81], v[82:83], off offset:1024 nt
	v_cvt_pk_bf16_f32 v82, v12, v13
	s_waitcnt lgkmcnt(0)
	v_add_f32_e32 v74, v72, v74
	v_xor_b32_e32 v72, 4, v68
	v_cmp_lt_i32_e32 vcc, v72, v78
	v_cvt_pk_bf16_f32 v83, v14, v15
	global_store_dwordx2 v[80:81], v[82:83], off offset:1536 nt
	s_nop 0
	v_cndmask_b32_e32 v72, v68, v72, vcc
	v_lshlrev_b32_e32 v72, 2, v72
	ds_bpermute_b32 v75, v72, v74
	s_waitcnt lgkmcnt(0)
	v_add_f32_e32 v75, v74, v75
	v_xor_b32_e32 v74, 8, v68
	v_cmp_lt_i32_e32 vcc, v74, v78
	s_nop 1
	v_cndmask_b32_e32 v74, v68, v74, vcc
	v_lshlrev_b32_e32 v74, 2, v74
	ds_bpermute_b32 v79, v74, v75
	s_waitcnt lgkmcnt(0)
	v_add_f32_e32 v79, v75, v79
	v_xor_b32_e32 v75, 16, v68
	v_cmp_lt_i32_e32 vcc, v75, v78
	s_nop 1
	v_cndmask_b32_e32 v75, v68, v75, vcc
	v_lshlrev_b32_e32 v75, 2, v75
	ds_bpermute_b32 v84, v75, v79
	v_cmp_lt_i32_e32 vcc, v76, v78
	s_waitcnt lgkmcnt(0)
	v_add_f32_e32 v77, v79, v84
	v_cndmask_b32_e32 v76, v68, v76, vcc
	v_lshlrev_b32_e32 v76, 2, v76
	ds_bpermute_b32 v78, v76, v77
	s_and_saveexec_b64 s[20:21], s[4:5]
	s_cbranch_execz .LBB0_210
	s_waitcnt lgkmcnt(0)
	v_add_f32_e32 v77, v77, v78
	v_fmamk_f32 v77, v77, 0x3a800000, v69
	v_rsq_f32_e32 v77, v77
	s_lshl_b64 s[28:29], s[14:15], 2
	s_add_u32 s28, s22, s28
	s_addc_u32 s29, s23, s29
	global_store_dword v73, v77, s[28:29]
.LBB0_210:
	s_or_b64 exec, exec, s[20:21]
	v_mul_f32_e32 v77, v17, v17
	s_waitcnt lgkmcnt(0)
	v_mul_f32_e32 v78, v19, v19
	v_fmac_f32_e32 v77, v16, v16
	v_fmac_f32_e32 v78, v18, v18
	v_add_f32_e32 v77, v77, v78
	v_mul_f32_e32 v78, v21, v21
	v_mul_f32_e32 v79, v23, v23
	v_fmac_f32_e32 v78, v20, v20
	v_fmac_f32_e32 v79, v22, v22
	v_add_f32_e32 v78, v78, v79
	v_add_f32_e32 v77, v77, v78
	v_mul_f32_e32 v78, v25, v25
	v_mul_f32_e32 v79, v27, v27
	v_fmac_f32_e32 v78, v24, v24
	v_fmac_f32_e32 v79, v26, v26
	v_add_f32_e32 v78, v78, v79
	v_add_f32_e32 v77, v78, v77
	v_mul_f32_e32 v78, v29, v29
	v_mul_f32_e32 v79, v31, v31
	v_fmac_f32_e32 v78, v28, v28
	v_fmac_f32_e32 v79, v30, v30
	v_add_f32_e32 v78, v78, v79
	v_add_f32_e32 v77, v78, v77
	ds_bpermute_b32 v78, v70, v77
	s_ashr_i32 s9, s8, 31
	s_lshl_b64 s[20:21], s[8:9], 11
	v_lshl_add_u64 v[80:81], v[66:67], 0, s[20:21]
	s_waitcnt lgkmcnt(0)
	v_add_f32_e32 v77, v77, v78
	ds_bpermute_b32 v78, v71, v77
	s_waitcnt lgkmcnt(0)
	v_add_f32_e32 v77, v77, v78
	ds_bpermute_b32 v78, v72, v77
	s_waitcnt lgkmcnt(0)
	v_add_f32_e32 v77, v77, v78
	ds_bpermute_b32 v82, v74, v77
	v_cvt_pk_bf16_f32 v78, v16, v17
	v_cvt_pk_bf16_f32 v79, v18, v19
	global_store_dwordx2 v[80:81], v[78:79], off nt
	v_cvt_pk_bf16_f32 v78, v20, v21
	s_waitcnt lgkmcnt(0)
	v_add_f32_e32 v77, v77, v82
	ds_bpermute_b32 v84, v75, v77
	v_cvt_pk_bf16_f32 v79, v22, v23
	global_store_dwordx2 v[80:81], v[78:79], off offset:512 nt
	v_cvt_pk_bf16_f32 v82, v24, v25
	v_cvt_pk_bf16_f32 v83, v26, v27
	s_waitcnt lgkmcnt(0)
	v_add_f32_e32 v77, v77, v84
	ds_bpermute_b32 v78, v76, v77
	global_store_dwordx2 v[80:81], v[82:83], off offset:1024 nt
	v_cvt_pk_bf16_f32 v82, v28, v29
	v_cvt_pk_bf16_f32 v83, v30, v31
	global_store_dwordx2 v[80:81], v[82:83], off offset:1536 nt
	s_and_saveexec_b64 s[20:21], s[4:5]
	s_cbranch_execnz .LBB0_213
	s_or_b64 exec, exec, s[20:21]
	s_waitcnt vmcnt(9)
	s_add_i32 s20, s24, s6
	s_cmpk_gt_i32 s20, 0x7fff
	s_cbranch_scc0 .LBB0_214

.LBB0_213:
	s_waitcnt lgkmcnt(0)
	v_add_f32_e32 v77, v77, v78
	v_fmamk_f32 v77, v77, 0x3a800000, v69
	v_rsq_f32_e32 v77, v77
	s_lshl_b64 s[28:29], s[8:9], 2
	s_add_u32 s28, s22, s28
	s_addc_u32 s29, s23, s29
	global_store_dword v73, v77, s[28:29]
	s_waitcnt vmcnt(10)
	s_or_b64 exec, exec, s[20:21]
	s_add_i32 s20, s24, s6
	s_cmpk_gt_i32 s20, 0x7fff
	s_cbranch_scc1 .LBB0_212
